# GEMM loops: first K-iteration peeled with C=0 first-touch MFMAs, 128 accumulator-zeroing v_mov per tile removed (all three loops)
# speedup vs baseline: 1.0092x; 1.0047x over previous
.LBB0_123:
	s_ashr_i32 s23, s22, 31
	s_lshl_b64 s[24:25], s[22:23], 19
	s_add_u32 s24, s12, s24
	s_addc_u32 s25, s13, s25
	s_and_b64 s[26:27], s[6:7], exec
	s_cselect_b32 s23, s25, s35
	s_cselect_b32 s29, s24, s34
	s_ashr_i32 s21, s20, 31
	s_lshl_b64 s[26:27], s[20:21], 19
	s_add_u32 s26, s10, s26
	s_addc_u32 s27, s11, s27
	s_and_b64 s[36:37], s[6:7], exec
	s_cselect_b32 s21, s27, s9
	s_cselect_b32 s31, s26, s8
	s_add_u32 s46, s8, 0x100
	s_addc_u32 s47, s9, 0
	s_add_u32 s8, s34, 0x40080
	s_addc_u32 s9, s35, 0
	s_mov_b32 s48, -2
	s_waitcnt vmcnt(0)
	s_add_u32 s34, s8, 0xfffc0080
	s_addc_u32 s35, s9, -1
	s_add_i32 s49, 0, 0x10000
	s_cmp_eq_u32 s48, 12
	s_cselect_b32 s37, s23, s35
	s_cselect_b32 s36, s29, s34
	s_cselect_b32 s35, s21, s47
	s_cselect_b32 s34, s31, s46
	s_add_i32 s52, 0, 0x14000
	v_add_u32_e32 v76, s49, v233
	v_add_u32_e32 v132, s52, v233
	ds_read_b128 v[56:59], v76
	ds_read_b128 v[60:63], v76 offset:1024
	ds_read_b128 v[68:71], v76 offset:2048
	ds_read_b128 v[76:79], v76 offset:3072
	ds_read_b128 v[104:107], v132
	ds_read_b128 v[108:111], v132 offset:1024
	ds_read_b128 v[124:127], v132 offset:2048
	ds_read_b128 v[132:135], v132 offset:3072
	v_lshl_add_u64 v[208:209], s[8:9], 0, v[206:207]
	s_add_i32 m0, s39, 0xc000
	ds_read_b128 v[152:155], v235
	ds_read_b128 v[156:159], v235 offset:1024
	ds_read_b128 v[168:171], v235 offset:2048
	ds_read_b128 v[172:175], v235 offset:3072
	ds_read_b128 v[176:179], v235 offset:4096
	ds_read_b128 v[180:183], v235 offset:5120
	ds_read_b128 v[184:187], v235 offset:6144
	ds_read_b128 v[188:191], v235 offset:7168
	global_load_lds_dwordx4 v[208:209], off
	v_lshl_add_u64 v[208:209], s[8:9], 0, v[204:205]
	s_add_i32 m0, s39, 0xe000
	s_nop 0
	global_load_lds_dwordx4 v[208:209], off
	s_waitcnt vmcnt(8)
	s_waitcnt lgkmcnt(0)
	s_barrier
	s_setprio 1
	s_waitcnt lgkmcnt(0)
	v_mfma_f32_16x16x32_bf16 v[164:167], v[56:59], v[152:155], 0
	v_mfma_f32_16x16x32_bf16 v[160:163], v[68:71], v[152:155], 0
	v_mfma_f32_16x16x32_bf16 v[140:143], v[56:59], v[168:171], 0
	v_mfma_f32_16x16x32_bf16 v[136:139], v[68:71], v[168:171], 0
	v_mfma_f32_16x16x32_bf16 v[116:119], v[56:59], v[176:179], 0
	v_mfma_f32_16x16x32_bf16 v[112:115], v[68:71], v[176:179], 0
	v_mfma_f32_16x16x32_bf16 v[92:95], v[56:59], v[184:187], 0
	v_mfma_f32_16x16x32_bf16 v[88:91], v[68:71], v[184:187], 0
	v_mfma_f32_16x16x32_bf16 v[164:167], v[60:63], v[156:159], v[164:167]
	v_mfma_f32_16x16x32_bf16 v[160:163], v[76:79], v[156:159], v[160:163]
	v_mfma_f32_16x16x32_bf16 v[140:143], v[60:63], v[172:175], v[140:143]
	v_mfma_f32_16x16x32_bf16 v[136:139], v[76:79], v[172:175], v[136:139]
	v_mfma_f32_16x16x32_bf16 v[116:119], v[60:63], v[180:183], v[116:119]
	v_mfma_f32_16x16x32_bf16 v[112:115], v[76:79], v[180:183], v[112:115]
	v_mfma_f32_16x16x32_bf16 v[92:95], v[60:63], v[188:191], v[92:95]
	v_mfma_f32_16x16x32_bf16 v[88:91], v[76:79], v[188:191], v[88:91]
	s_setprio 0
	s_setprio 1
	v_mfma_f32_16x16x32_bf16 v[148:151], v[104:107], v[152:155], 0
	v_mfma_f32_16x16x32_bf16 v[144:147], v[124:127], v[152:155], 0
	v_mfma_f32_16x16x32_bf16 v[128:131], v[104:107], v[168:171], 0
	v_mfma_f32_16x16x32_bf16 v[120:123], v[124:127], v[168:171], 0
	v_mfma_f32_16x16x32_bf16 v[100:103], v[104:107], v[176:179], 0
	v_mfma_f32_16x16x32_bf16 v[96:99], v[124:127], v[176:179], 0
	v_mfma_f32_16x16x32_bf16 v[84:87], v[104:107], v[184:187], 0
	v_mfma_f32_16x16x32_bf16 v[80:83], v[124:127], v[184:187], 0
	v_mfma_f32_16x16x32_bf16 v[148:151], v[108:111], v[156:159], v[148:151]
	v_mfma_f32_16x16x32_bf16 v[144:147], v[132:135], v[156:159], v[144:147]
	v_mfma_f32_16x16x32_bf16 v[128:131], v[108:111], v[172:175], v[128:131]
	v_mfma_f32_16x16x32_bf16 v[120:123], v[132:135], v[172:175], v[120:123]
	v_mfma_f32_16x16x32_bf16 v[100:103], v[108:111], v[180:183], v[100:103]
	v_mfma_f32_16x16x32_bf16 v[96:99], v[132:135], v[180:183], v[96:99]
	v_mfma_f32_16x16x32_bf16 v[84:87], v[108:111], v[188:191], v[84:87]
	v_mfma_f32_16x16x32_bf16 v[80:83], v[132:135], v[188:191], v[80:83]
	s_setprio 0
	s_barrier
	s_nop 0
	s_add_i32 s49, s49, s38
	v_lshl_add_u64 v[208:209], s[34:35], 0, v[192:193]
	s_mov_b32 m0, s49
	ds_read_b128 v[152:155], v235 offset:16384
	ds_read_b128 v[156:159], v235 offset:17408
	ds_read_b128 v[168:171], v235 offset:18432
	ds_read_b128 v[172:175], v235 offset:19456
	ds_read_b128 v[176:179], v235 offset:20480
	ds_read_b128 v[180:183], v235 offset:21504
	ds_read_b128 v[184:187], v235 offset:22528
	ds_read_b128 v[188:191], v235 offset:23552
	global_load_lds_dwordx4 v[208:209], off
	s_add_i32 m0, s49, 0x2000
	s_add_u32 s50, s34, 0x40000
	v_lshl_add_u64 v[210:211], s[34:35], 0, v[200:201]
	s_addc_u32 s51, s35, 0
	s_add_i32 s49, s52, s38
	global_load_lds_dwordx4 v[210:211], off
	v_lshl_add_u64 v[212:213], s[50:51], 0, v[192:193]
	s_mov_b32 m0, s49
	v_lshl_add_u64 v[214:215], s[36:37], 0, v[198:199]
	global_load_lds_dwordx4 v[212:213], off
	v_lshl_add_u64 v[212:213], s[50:51], 0, v[200:201]
	s_add_i32 m0, s49, 0x2000
	s_nop 0
	global_load_lds_dwordx4 v[212:213], off
	v_lshl_add_u64 v[212:213], s[36:37], 0, v[196:197]
	s_mov_b32 m0, s39
	s_nop 0
	global_load_lds_dwordx4 v[212:213], off
	s_mov_b32 m0, s40
	s_nop 0
	global_load_lds_dwordx4 v[214:215], off
	s_waitcnt vmcnt(8)
	s_waitcnt lgkmcnt(0)
	s_barrier
	s_setprio 1
	s_waitcnt lgkmcnt(0)
	v_mfma_f32_16x16x32_bf16 v[72:75], v[56:59], v[152:155], 0
	v_mfma_f32_16x16x32_bf16 v[64:67], v[68:71], v[152:155], 0
	v_mfma_f32_16x16x32_bf16 v[44:47], v[56:59], v[168:171], 0
	v_mfma_f32_16x16x32_bf16 v[40:43], v[68:71], v[168:171], 0
	v_mfma_f32_16x16x32_bf16 v[28:31], v[56:59], v[176:179], 0
	v_mfma_f32_16x16x32_bf16 v[24:27], v[68:71], v[176:179], 0
	v_mfma_f32_16x16x32_bf16 v[12:15], v[56:59], v[184:187], 0
	v_mfma_f32_16x16x32_bf16 v[8:11], v[68:71], v[184:187], 0
	v_mfma_f32_16x16x32_bf16 v[72:75], v[60:63], v[156:159], v[72:75]
	v_mfma_f32_16x16x32_bf16 v[64:67], v[76:79], v[156:159], v[64:67]
	v_mfma_f32_16x16x32_bf16 v[44:47], v[60:63], v[172:175], v[44:47]
	v_mfma_f32_16x16x32_bf16 v[40:43], v[76:79], v[172:175], v[40:43]
	v_mfma_f32_16x16x32_bf16 v[28:31], v[60:63], v[180:183], v[28:31]
	v_mfma_f32_16x16x32_bf16 v[24:27], v[76:79], v[180:183], v[24:27]
	v_mfma_f32_16x16x32_bf16 v[12:15], v[60:63], v[188:191], v[12:15]
	v_mfma_f32_16x16x32_bf16 v[8:11], v[76:79], v[188:191], v[8:11]
	s_setprio 0
	s_setprio 1
	v_mfma_f32_16x16x32_bf16 v[52:55], v[104:107], v[152:155], 0
	v_mfma_f32_16x16x32_bf16 v[48:51], v[124:127], v[152:155], 0
	v_mfma_f32_16x16x32_bf16 v[36:39], v[104:107], v[168:171], 0
	v_mfma_f32_16x16x32_bf16 v[32:35], v[124:127], v[168:171], 0
	v_mfma_f32_16x16x32_bf16 v[20:23], v[104:107], v[176:179], 0
	v_mfma_f32_16x16x32_bf16 v[16:19], v[124:127], v[176:179], 0
	v_mfma_f32_16x16x32_bf16 v[4:7], v[104:107], v[184:187], 0
	v_mfma_f32_16x16x32_bf16 v[0:3], v[124:127], v[184:187], 0
	v_mfma_f32_16x16x32_bf16 v[52:55], v[108:111], v[156:159], v[52:55]
	v_mfma_f32_16x16x32_bf16 v[48:51], v[132:135], v[156:159], v[48:51]
	v_mfma_f32_16x16x32_bf16 v[36:39], v[108:111], v[172:175], v[36:39]
	v_mfma_f32_16x16x32_bf16 v[32:35], v[132:135], v[172:175], v[32:35]
	v_mfma_f32_16x16x32_bf16 v[20:23], v[108:111], v[180:183], v[20:23]
	v_mfma_f32_16x16x32_bf16 v[16:19], v[132:135], v[180:183], v[16:19]
	v_mfma_f32_16x16x32_bf16 v[4:7], v[108:111], v[188:191], v[4:7]
	v_mfma_f32_16x16x32_bf16 v[0:3], v[132:135], v[188:191], v[0:3]
	s_setprio 0
	s_barrier
	s_nop 0
	s_add_i32 s49, 0, 0x18000
	s_add_i32 s50, 0, 0x1c000
	v_add_u32_e32 v76, s49, v233
	v_add_u32_e32 v132, s50, v233
	ds_read_b128 v[56:59], v76
	ds_read_b128 v[60:63], v76 offset:1024
	ds_read_b128 v[68:71], v76 offset:2048
	ds_read_b128 v[76:79], v76 offset:3072
	ds_read_b128 v[104:107], v132
	ds_read_b128 v[108:111], v132 offset:1024
	ds_read_b128 v[124:127], v132 offset:2048
	ds_read_b128 v[132:135], v132 offset:3072
	s_add_u32 s36, s36, 0x40000
	s_addc_u32 s37, s37, 0
	s_mov_b32 m0, s41
	v_lshl_add_u64 v[216:217], s[36:37], 0, v[196:197]
	ds_read_b128 v[152:155], v235 offset:32768
	ds_read_b128 v[156:159], v235 offset:33792
	ds_read_b128 v[168:171], v235 offset:34816
	ds_read_b128 v[172:175], v235 offset:35840
	ds_read_b128 v[176:179], v235 offset:36864
	ds_read_b128 v[180:183], v235 offset:37888
	ds_read_b128 v[184:187], v235 offset:38912
	ds_read_b128 v[188:191], v235 offset:39936
	global_load_lds_dwordx4 v[216:217], off
	v_lshl_add_u64 v[216:217], s[36:37], 0, v[198:199]
	s_mov_b32 m0, s42
	s_nop 0
	global_load_lds_dwordx4 v[216:217], off
	s_waitcnt vmcnt(8)
	s_waitcnt lgkmcnt(0)
	s_barrier
	s_setprio 1
	s_waitcnt lgkmcnt(0)
	v_mfma_f32_16x16x32_bf16 v[164:167], v[56:59], v[152:155], v[164:167]
	v_mfma_f32_16x16x32_bf16 v[160:163], v[68:71], v[152:155], v[160:163]
	v_mfma_f32_16x16x32_bf16 v[140:143], v[56:59], v[168:171], v[140:143]
	v_mfma_f32_16x16x32_bf16 v[136:139], v[68:71], v[168:171], v[136:139]
	v_mfma_f32_16x16x32_bf16 v[116:119], v[56:59], v[176:179], v[116:119]
	v_mfma_f32_16x16x32_bf16 v[112:115], v[68:71], v[176:179], v[112:115]
	v_mfma_f32_16x16x32_bf16 v[92:95], v[56:59], v[184:187], v[92:95]
	v_mfma_f32_16x16x32_bf16 v[88:91], v[68:71], v[184:187], v[88:91]
	v_mfma_f32_16x16x32_bf16 v[164:167], v[60:63], v[156:159], v[164:167]
	v_mfma_f32_16x16x32_bf16 v[160:163], v[76:79], v[156:159], v[160:163]
	v_mfma_f32_16x16x32_bf16 v[140:143], v[60:63], v[172:175], v[140:143]
	v_mfma_f32_16x16x32_bf16 v[136:139], v[76:79], v[172:175], v[136:139]
	v_mfma_f32_16x16x32_bf16 v[116:119], v[60:63], v[180:183], v[116:119]
	v_mfma_f32_16x16x32_bf16 v[112:115], v[76:79], v[180:183], v[112:115]
	v_mfma_f32_16x16x32_bf16 v[92:95], v[60:63], v[188:191], v[92:95]
	v_mfma_f32_16x16x32_bf16 v[88:91], v[76:79], v[188:191], v[88:91]
	s_setprio 0
	s_setprio 1
	v_mfma_f32_16x16x32_bf16 v[148:151], v[104:107], v[152:155], v[148:151]
	v_mfma_f32_16x16x32_bf16 v[144:147], v[124:127], v[152:155], v[144:147]
	v_mfma_f32_16x16x32_bf16 v[128:131], v[104:107], v[168:171], v[128:131]
	v_mfma_f32_16x16x32_bf16 v[120:123], v[124:127], v[168:171], v[120:123]
	v_mfma_f32_16x16x32_bf16 v[100:103], v[104:107], v[176:179], v[100:103]
	v_mfma_f32_16x16x32_bf16 v[96:99], v[124:127], v[176:179], v[96:99]
	v_mfma_f32_16x16x32_bf16 v[84:87], v[104:107], v[184:187], v[84:87]
	v_mfma_f32_16x16x32_bf16 v[80:83], v[124:127], v[184:187], v[80:83]
	v_mfma_f32_16x16x32_bf16 v[148:151], v[108:111], v[156:159], v[148:151]
	v_mfma_f32_16x16x32_bf16 v[144:147], v[132:135], v[156:159], v[144:147]
	v_mfma_f32_16x16x32_bf16 v[128:131], v[108:111], v[172:175], v[128:131]
	v_mfma_f32_16x16x32_bf16 v[120:123], v[132:135], v[172:175], v[120:123]
	v_mfma_f32_16x16x32_bf16 v[100:103], v[108:111], v[180:183], v[100:103]
	v_mfma_f32_16x16x32_bf16 v[96:99], v[132:135], v[180:183], v[96:99]
	v_mfma_f32_16x16x32_bf16 v[84:87], v[108:111], v[188:191], v[84:87]
	v_mfma_f32_16x16x32_bf16 v[80:83], v[132:135], v[188:191], v[80:83]
	s_setprio 0
	s_barrier
	s_add_i32 s36, s49, s38
	v_lshl_add_u64 v[208:209], v[208:209], 0, s[2:3]
	s_mov_b32 m0, s36
	ds_read_b128 v[152:155], v235 offset:49152
	ds_read_b128 v[156:159], v235 offset:50176
	ds_read_b128 v[168:171], v235 offset:51200
	ds_read_b128 v[172:175], v235 offset:52224
	ds_read_b128 v[176:179], v235 offset:53248
	ds_read_b128 v[180:183], v235 offset:54272
	ds_read_b128 v[184:187], v235 offset:55296
	ds_read_b128 v[188:191], v235 offset:56320
	global_load_lds_dwordx4 v[208:209], off
	s_add_i32 m0, s36, 0x2000
	s_add_u32 s34, s34, 0x40080
	v_lshl_add_u64 v[208:209], v[210:211], 0, s[2:3]
	s_addc_u32 s35, s35, 0
	s_add_i32 s36, s50, s38
	global_load_lds_dwordx4 v[208:209], off
	v_lshl_add_u64 v[208:209], s[34:35], 0, v[192:193]
	s_mov_b32 m0, s36
	s_nop 0
	global_load_lds_dwordx4 v[208:209], off
	v_lshl_add_u64 v[208:209], s[34:35], 0, v[200:201]
	s_add_i32 m0, s36, 0x2000
	s_nop 0
	global_load_lds_dwordx4 v[208:209], off
	v_lshl_add_u64 v[208:209], v[212:213], 0, s[2:3]
	s_mov_b32 m0, s43
	s_nop 0
	global_load_lds_dwordx4 v[208:209], off
	v_lshl_add_u64 v[208:209], v[214:215], 0, s[2:3]
	s_mov_b32 m0, s44
	s_nop 0
	global_load_lds_dwordx4 v[208:209], off
	s_waitcnt vmcnt(8)
	s_waitcnt lgkmcnt(0)
	s_barrier
	s_setprio 1
	s_waitcnt lgkmcnt(0)
	v_mfma_f32_16x16x32_bf16 v[72:75], v[56:59], v[152:155], v[72:75]
	v_mfma_f32_16x16x32_bf16 v[64:67], v[68:71], v[152:155], v[64:67]
	v_mfma_f32_16x16x32_bf16 v[44:47], v[56:59], v[168:171], v[44:47]
	v_mfma_f32_16x16x32_bf16 v[40:43], v[68:71], v[168:171], v[40:43]
	v_mfma_f32_16x16x32_bf16 v[28:31], v[56:59], v[176:179], v[28:31]
	v_mfma_f32_16x16x32_bf16 v[24:27], v[68:71], v[176:179], v[24:27]
	v_mfma_f32_16x16x32_bf16 v[12:15], v[56:59], v[184:187], v[12:15]
	v_mfma_f32_16x16x32_bf16 v[8:11], v[68:71], v[184:187], v[8:11]
	v_mfma_f32_16x16x32_bf16 v[72:75], v[60:63], v[156:159], v[72:75]
	v_mfma_f32_16x16x32_bf16 v[64:67], v[76:79], v[156:159], v[64:67]
	v_mfma_f32_16x16x32_bf16 v[44:47], v[60:63], v[172:175], v[44:47]
	v_mfma_f32_16x16x32_bf16 v[40:43], v[76:79], v[172:175], v[40:43]
	v_mfma_f32_16x16x32_bf16 v[28:31], v[60:63], v[180:183], v[28:31]
	v_mfma_f32_16x16x32_bf16 v[24:27], v[76:79], v[180:183], v[24:27]
	v_mfma_f32_16x16x32_bf16 v[12:15], v[60:63], v[188:191], v[12:15]
	v_mfma_f32_16x16x32_bf16 v[8:11], v[76:79], v[188:191], v[8:11]
	s_setprio 0
	s_setprio 1
	v_mfma_f32_16x16x32_bf16 v[52:55], v[104:107], v[152:155], v[52:55]
	v_mfma_f32_16x16x32_bf16 v[48:51], v[124:127], v[152:155], v[48:51]
	v_mfma_f32_16x16x32_bf16 v[36:39], v[104:107], v[168:171], v[36:39]
	v_mfma_f32_16x16x32_bf16 v[32:35], v[124:127], v[168:171], v[32:35]
	v_mfma_f32_16x16x32_bf16 v[20:23], v[104:107], v[176:179], v[20:23]
	v_mfma_f32_16x16x32_bf16 v[16:19], v[124:127], v[176:179], v[16:19]
	v_mfma_f32_16x16x32_bf16 v[4:7], v[104:107], v[184:187], v[4:7]
	v_mfma_f32_16x16x32_bf16 v[0:3], v[124:127], v[184:187], v[0:3]
	v_mfma_f32_16x16x32_bf16 v[52:55], v[108:111], v[156:159], v[52:55]
	v_mfma_f32_16x16x32_bf16 v[48:51], v[132:135], v[156:159], v[48:51]
	v_mfma_f32_16x16x32_bf16 v[36:39], v[108:111], v[172:175], v[36:39]
	v_mfma_f32_16x16x32_bf16 v[32:35], v[132:135], v[172:175], v[32:35]
	v_mfma_f32_16x16x32_bf16 v[20:23], v[108:111], v[180:183], v[20:23]
	v_mfma_f32_16x16x32_bf16 v[16:19], v[132:135], v[180:183], v[16:19]
	v_mfma_f32_16x16x32_bf16 v[4:7], v[108:111], v[188:191], v[4:7]
	v_mfma_f32_16x16x32_bf16 v[0:3], v[132:135], v[188:191], v[0:3]
	s_setprio 0
	s_barrier
	s_add_i32 s48, s48, 2
	s_add_u32 s46, s46, 0x100
	s_addc_u32 s47, s47, 0
	s_add_u32 s8, s8, 0x100
	s_addc_u32 s9, s9, 0
	s_cmp_gt_u32 s48, 13
	s_cbranch_scc0 .LBB0_124
	s_branch .Lpeel_exit_124

.Lpeel_exit_124:
	s_and_b64 vcc, exec, s[16:17]
	s_cbranch_vccz .LBB0_127
	s_barrier

.LBB0_573:
	s_ashr_i32 s25, s24, 31
	s_lshl_b64 s[26:27], s[24:25], 19
	s_add_u32 s26, s8, s26
	s_addc_u32 s27, s9, s27
	s_and_b64 s[28:29], s[4:5], exec
	s_cselect_b32 s25, s27, s35
	s_cselect_b32 s49, s26, s34
	s_ashr_i32 s23, s22, 31
	s_lshl_b64 s[28:29], s[22:23], 19
	s_add_u32 s28, s10, s28
	s_addc_u32 s29, s11, s29
	s_and_b64 s[36:37], s[4:5], exec
	s_cselect_b32 s23, s29, s31
	s_cselect_b32 s50, s28, s30
	s_add_u32 s51, s30, 0x100
	s_addc_u32 s52, s31, 0
	s_add_u32 s30, s34, 0x40080
	s_addc_u32 s31, s35, 0
	s_mov_b32 s53, -2
	s_waitcnt lgkmcnt(0)
	s_nop 0
	s_add_u32 s34, s30, 0xfffc0080
	s_addc_u32 s35, s31, -1
	s_add_i32 s54, 0, 0x10000
	s_cmp_eq_u32 s53, 12
	s_cselect_b32 s37, s25, s35
	s_cselect_b32 s36, s49, s34
	v_add_u32_e32 v138, s54, v141
	s_cselect_b32 s35, s23, s52
	s_cselect_b32 s34, s50, s51
	s_add_i32 s61, 0, 0x14000
	ds_read_b128 v[144:147], v138
	ds_read_b128 v[148:151], v138 offset:1024
	ds_read_b128 v[152:155], v138 offset:2048
	ds_read_b128 v[156:159], v138 offset:3072
	v_add_u32_e32 v138, s61, v141
	ds_read_b128 v[160:163], v138
	ds_read_b128 v[164:167], v138 offset:1024
	ds_read_b128 v[168:171], v138 offset:2048
	ds_read_b128 v[172:175], v138 offset:3072
	s_add_i32 m0, s40, 0xc000
	ds_read_b128 v[176:179], v143
	ds_read_b128 v[180:183], v143 offset:1024
	ds_read_b128 v[184:187], v143 offset:2048
	ds_read_b128 v[188:191], v143 offset:3072
	ds_read_b128 v[196:199], v143 offset:4096
	ds_read_b128 v[200:203], v143 offset:5120
	ds_read_b128 v[204:207], v143 offset:6144
	ds_read_b128 v[208:211], v143 offset:7168
	global_load_lds_dwordx4 v136, s[30:31]
	s_add_i32 m0, s40, 0xe000
	s_nop 0
	global_load_lds_dwordx4 v134, s[30:31]
	s_waitcnt vmcnt(8)
	s_waitcnt lgkmcnt(0)
	s_barrier
	s_setprio 1
	s_waitcnt lgkmcnt(0)
	v_mfma_f32_16x16x32_bf16 v[124:127], v[144:147], v[176:179], 0
	v_mfma_f32_16x16x32_bf16 v[120:123], v[152:155], v[176:179], 0
	v_mfma_f32_16x16x32_bf16 v[108:111], v[144:147], v[184:187], 0
	v_mfma_f32_16x16x32_bf16 v[104:107], v[152:155], v[184:187], 0
	v_mfma_f32_16x16x32_bf16 v[92:95], v[144:147], v[196:199], 0
	v_mfma_f32_16x16x32_bf16 v[88:91], v[152:155], v[196:199], 0
	v_mfma_f32_16x16x32_bf16 v[76:79], v[144:147], v[204:207], 0
	v_mfma_f32_16x16x32_bf16 v[72:75], v[152:155], v[204:207], 0
	v_mfma_f32_16x16x32_bf16 v[124:127], v[148:151], v[180:183], v[124:127]
	v_mfma_f32_16x16x32_bf16 v[120:123], v[156:159], v[180:183], v[120:123]
	v_mfma_f32_16x16x32_bf16 v[108:111], v[148:151], v[188:191], v[108:111]
	v_mfma_f32_16x16x32_bf16 v[104:107], v[156:159], v[188:191], v[104:107]
	v_mfma_f32_16x16x32_bf16 v[92:95], v[148:151], v[200:203], v[92:95]
	v_mfma_f32_16x16x32_bf16 v[88:91], v[156:159], v[200:203], v[88:91]
	v_mfma_f32_16x16x32_bf16 v[76:79], v[148:151], v[208:211], v[76:79]
	v_mfma_f32_16x16x32_bf16 v[72:75], v[156:159], v[208:211], v[72:75]
	s_setprio 0
	s_setprio 1
	v_mfma_f32_16x16x32_bf16 v[116:119], v[160:163], v[176:179], 0
	v_mfma_f32_16x16x32_bf16 v[112:115], v[168:171], v[176:179], 0
	v_mfma_f32_16x16x32_bf16 v[100:103], v[160:163], v[184:187], 0
	v_mfma_f32_16x16x32_bf16 v[96:99], v[168:171], v[184:187], 0
	v_mfma_f32_16x16x32_bf16 v[84:87], v[160:163], v[196:199], 0
	v_mfma_f32_16x16x32_bf16 v[80:83], v[168:171], v[196:199], 0
	v_mfma_f32_16x16x32_bf16 v[68:71], v[160:163], v[204:207], 0
	v_mfma_f32_16x16x32_bf16 v[64:67], v[168:171], v[204:207], 0
	v_mfma_f32_16x16x32_bf16 v[116:119], v[164:167], v[180:183], v[116:119]
	v_mfma_f32_16x16x32_bf16 v[112:115], v[172:175], v[180:183], v[112:115]
	v_mfma_f32_16x16x32_bf16 v[100:103], v[164:167], v[188:191], v[100:103]
	v_mfma_f32_16x16x32_bf16 v[96:99], v[172:175], v[188:191], v[96:99]
	v_mfma_f32_16x16x32_bf16 v[84:87], v[164:167], v[200:203], v[84:87]
	v_mfma_f32_16x16x32_bf16 v[80:83], v[172:175], v[200:203], v[80:83]
	v_mfma_f32_16x16x32_bf16 v[68:71], v[164:167], v[208:211], v[68:71]
	v_mfma_f32_16x16x32_bf16 v[64:67], v[172:175], v[208:211], v[64:67]
	s_setprio 0
	s_barrier
	s_add_i32 s54, s54, s39
	s_mov_b32 m0, s54
	ds_read_b128 v[176:179], v143 offset:16384
	ds_read_b128 v[180:183], v143 offset:17408
	ds_read_b128 v[184:187], v143 offset:18432
	ds_read_b128 v[188:191], v143 offset:19456
	ds_read_b128 v[196:199], v143 offset:20480
	ds_read_b128 v[200:203], v143 offset:21504
	ds_read_b128 v[204:207], v143 offset:22528
	ds_read_b128 v[208:211], v143 offset:23552
	global_load_lds_dwordx4 v192, s[34:35]
	s_add_i32 m0, s54, 0x2000
	s_add_u32 s54, s34, 0x40000
	s_addc_u32 s55, s35, 0
	s_add_i32 s61, s61, s39
	global_load_lds_dwordx4 v128, s[34:35]
	s_mov_b32 m0, s61
	s_nop 0
	global_load_lds_dwordx4 v192, s[54:55]
	s_add_i32 m0, s61, 0x2000
	s_nop 0
	global_load_lds_dwordx4 v128, s[54:55]
	s_mov_b32 m0, s40
	s_nop 0
	global_load_lds_dwordx4 v132, s[36:37]
	s_mov_b32 m0, s41
	s_nop 0
	global_load_lds_dwordx4 v130, s[36:37]
	s_waitcnt vmcnt(8)
	s_waitcnt lgkmcnt(0)
	s_barrier
	s_setprio 1
	s_waitcnt lgkmcnt(0)
	v_mfma_f32_16x16x32_bf16 v[60:63], v[144:147], v[176:179], 0
	v_mfma_f32_16x16x32_bf16 v[56:59], v[152:155], v[176:179], 0
	v_mfma_f32_16x16x32_bf16 v[44:47], v[144:147], v[184:187], 0
	v_mfma_f32_16x16x32_bf16 v[40:43], v[152:155], v[184:187], 0
	v_mfma_f32_16x16x32_bf16 v[28:31], v[144:147], v[196:199], 0
	v_mfma_f32_16x16x32_bf16 v[24:27], v[152:155], v[196:199], 0
	v_mfma_f32_16x16x32_bf16 v[12:15], v[144:147], v[204:207], 0
	v_mfma_f32_16x16x32_bf16 v[8:11], v[152:155], v[204:207], 0
	v_mfma_f32_16x16x32_bf16 v[60:63], v[148:151], v[180:183], v[60:63]
	v_mfma_f32_16x16x32_bf16 v[56:59], v[156:159], v[180:183], v[56:59]
	v_mfma_f32_16x16x32_bf16 v[44:47], v[148:151], v[188:191], v[44:47]
	v_mfma_f32_16x16x32_bf16 v[40:43], v[156:159], v[188:191], v[40:43]
	v_mfma_f32_16x16x32_bf16 v[28:31], v[148:151], v[200:203], v[28:31]
	v_mfma_f32_16x16x32_bf16 v[24:27], v[156:159], v[200:203], v[24:27]
	v_mfma_f32_16x16x32_bf16 v[12:15], v[148:151], v[208:211], v[12:15]
	v_mfma_f32_16x16x32_bf16 v[8:11], v[156:159], v[208:211], v[8:11]
	s_setprio 0
	s_setprio 1
	v_mfma_f32_16x16x32_bf16 v[52:55], v[160:163], v[176:179], 0
	v_mfma_f32_16x16x32_bf16 v[48:51], v[168:171], v[176:179], 0
	v_mfma_f32_16x16x32_bf16 v[36:39], v[160:163], v[184:187], 0
	v_mfma_f32_16x16x32_bf16 v[32:35], v[168:171], v[184:187], 0
	v_mfma_f32_16x16x32_bf16 v[20:23], v[160:163], v[196:199], 0
	v_mfma_f32_16x16x32_bf16 v[16:19], v[168:171], v[196:199], 0
	v_mfma_f32_16x16x32_bf16 v[4:7], v[160:163], v[204:207], 0
	v_mfma_f32_16x16x32_bf16 v[0:3], v[168:171], v[204:207], 0
	v_mfma_f32_16x16x32_bf16 v[52:55], v[164:167], v[180:183], v[52:55]
	v_mfma_f32_16x16x32_bf16 v[48:51], v[172:175], v[180:183], v[48:51]
	v_mfma_f32_16x16x32_bf16 v[36:39], v[164:167], v[188:191], v[36:39]
	v_mfma_f32_16x16x32_bf16 v[32:35], v[172:175], v[188:191], v[32:35]
	v_mfma_f32_16x16x32_bf16 v[20:23], v[164:167], v[200:203], v[20:23]
	v_mfma_f32_16x16x32_bf16 v[16:19], v[172:175], v[200:203], v[16:19]
	v_mfma_f32_16x16x32_bf16 v[4:7], v[164:167], v[208:211], v[4:7]
	v_mfma_f32_16x16x32_bf16 v[0:3], v[172:175], v[208:211], v[0:3]
	s_setprio 0
	s_barrier
	s_nop 0
	s_add_i32 s54, 0, 0x18000
	s_add_i32 s55, 0, 0x1c000
	v_add_u32_e32 v156, s54, v141
	v_add_u32_e32 v172, s55, v141
	ds_read_b128 v[144:147], v156
	ds_read_b128 v[148:151], v156 offset:1024
	ds_read_b128 v[152:155], v156 offset:2048
	ds_read_b128 v[156:159], v156 offset:3072
	ds_read_b128 v[160:163], v172
	ds_read_b128 v[164:167], v172 offset:1024
	ds_read_b128 v[168:171], v172 offset:2048
	ds_read_b128 v[172:175], v172 offset:3072
	s_add_u32 s36, s36, 0x40000
	s_addc_u32 s37, s37, 0
	s_mov_b32 m0, s42
	ds_read_b128 v[176:179], v143 offset:32768
	ds_read_b128 v[180:183], v143 offset:33792
	ds_read_b128 v[184:187], v143 offset:34816
	ds_read_b128 v[188:191], v143 offset:35840
	ds_read_b128 v[196:199], v143 offset:36864
	ds_read_b128 v[200:203], v143 offset:37888
	ds_read_b128 v[204:207], v143 offset:38912
	ds_read_b128 v[208:211], v143 offset:39936
	global_load_lds_dwordx4 v132, s[36:37]
	s_mov_b32 m0, s43
	s_nop 0
	global_load_lds_dwordx4 v130, s[36:37]
	s_waitcnt vmcnt(8)
	s_waitcnt lgkmcnt(0)
	s_barrier
	s_setprio 1
	s_waitcnt lgkmcnt(0)
	v_mfma_f32_16x16x32_bf16 v[124:127], v[144:147], v[176:179], v[124:127]
	v_mfma_f32_16x16x32_bf16 v[120:123], v[152:155], v[176:179], v[120:123]
	v_mfma_f32_16x16x32_bf16 v[108:111], v[144:147], v[184:187], v[108:111]
	v_mfma_f32_16x16x32_bf16 v[104:107], v[152:155], v[184:187], v[104:107]
	v_mfma_f32_16x16x32_bf16 v[92:95], v[144:147], v[196:199], v[92:95]
	v_mfma_f32_16x16x32_bf16 v[88:91], v[152:155], v[196:199], v[88:91]
	v_mfma_f32_16x16x32_bf16 v[76:79], v[144:147], v[204:207], v[76:79]
	v_mfma_f32_16x16x32_bf16 v[72:75], v[152:155], v[204:207], v[72:75]
	v_mfma_f32_16x16x32_bf16 v[124:127], v[148:151], v[180:183], v[124:127]
	v_mfma_f32_16x16x32_bf16 v[120:123], v[156:159], v[180:183], v[120:123]
	v_mfma_f32_16x16x32_bf16 v[108:111], v[148:151], v[188:191], v[108:111]
	v_mfma_f32_16x16x32_bf16 v[104:107], v[156:159], v[188:191], v[104:107]
	v_mfma_f32_16x16x32_bf16 v[92:95], v[148:151], v[200:203], v[92:95]
	v_mfma_f32_16x16x32_bf16 v[88:91], v[156:159], v[200:203], v[88:91]
	v_mfma_f32_16x16x32_bf16 v[76:79], v[148:151], v[208:211], v[76:79]
	v_mfma_f32_16x16x32_bf16 v[72:75], v[156:159], v[208:211], v[72:75]
	s_setprio 0
	s_setprio 1
	v_mfma_f32_16x16x32_bf16 v[116:119], v[160:163], v[176:179], v[116:119]
	v_mfma_f32_16x16x32_bf16 v[112:115], v[168:171], v[176:179], v[112:115]
	v_mfma_f32_16x16x32_bf16 v[100:103], v[160:163], v[184:187], v[100:103]
	v_mfma_f32_16x16x32_bf16 v[96:99], v[168:171], v[184:187], v[96:99]
	v_mfma_f32_16x16x32_bf16 v[84:87], v[160:163], v[196:199], v[84:87]
	v_mfma_f32_16x16x32_bf16 v[80:83], v[168:171], v[196:199], v[80:83]
	v_mfma_f32_16x16x32_bf16 v[68:71], v[160:163], v[204:207], v[68:71]
	v_mfma_f32_16x16x32_bf16 v[64:67], v[168:171], v[204:207], v[64:67]
	v_mfma_f32_16x16x32_bf16 v[116:119], v[164:167], v[180:183], v[116:119]
	v_mfma_f32_16x16x32_bf16 v[112:115], v[172:175], v[180:183], v[112:115]
	v_mfma_f32_16x16x32_bf16 v[100:103], v[164:167], v[188:191], v[100:103]
	v_mfma_f32_16x16x32_bf16 v[96:99], v[172:175], v[188:191], v[96:99]
	v_mfma_f32_16x16x32_bf16 v[84:87], v[164:167], v[200:203], v[84:87]
	v_mfma_f32_16x16x32_bf16 v[80:83], v[172:175], v[200:203], v[80:83]
	v_mfma_f32_16x16x32_bf16 v[68:71], v[164:167], v[208:211], v[68:71]
	v_mfma_f32_16x16x32_bf16 v[64:67], v[172:175], v[208:211], v[64:67]
	s_setprio 0
	s_barrier
	s_nop 0
	s_add_u32 s36, s36, 0xfffc0080
	s_addc_u32 s37, s37, -1
	s_add_u32 s34, s34, 0x80
	s_addc_u32 s35, s35, 0
	s_add_i32 m0, s54, s39
	ds_read_b128 v[176:179], v143 offset:49152
	ds_read_b128 v[180:183], v143 offset:50176
	ds_read_b128 v[184:187], v143 offset:51200
	ds_read_b128 v[188:191], v143 offset:52224
	ds_read_b128 v[196:199], v143 offset:53248
	ds_read_b128 v[200:203], v143 offset:54272
	ds_read_b128 v[204:207], v143 offset:55296
	ds_read_b128 v[208:211], v143 offset:56320
	global_load_lds_dwordx4 v192, s[34:35]
	s_add_i32 m0, m0, 0x2000
	s_nop 0
	global_load_lds_dwordx4 v128, s[34:35]
	s_add_u32 s34, s34, 0x40000
	s_addc_u32 s35, s35, 0
	s_add_i32 m0, s55, s39
	s_nop 0
	global_load_lds_dwordx4 v192, s[34:35]
	s_add_i32 m0, m0, 0x2000
	s_nop 0
	global_load_lds_dwordx4 v128, s[34:35]
	s_mov_b32 m0, s44
	s_nop 0
	global_load_lds_dwordx4 v132, s[36:37]
	s_mov_b32 m0, s45
	s_nop 0
	global_load_lds_dwordx4 v130, s[36:37]
	s_waitcnt vmcnt(8)
	s_waitcnt lgkmcnt(0)
	s_barrier
	s_setprio 1
	s_waitcnt lgkmcnt(0)
	v_mfma_f32_16x16x32_bf16 v[60:63], v[144:147], v[176:179], v[60:63]
	v_mfma_f32_16x16x32_bf16 v[56:59], v[152:155], v[176:179], v[56:59]
	v_mfma_f32_16x16x32_bf16 v[44:47], v[144:147], v[184:187], v[44:47]
	v_mfma_f32_16x16x32_bf16 v[40:43], v[152:155], v[184:187], v[40:43]
	v_mfma_f32_16x16x32_bf16 v[28:31], v[144:147], v[196:199], v[28:31]
	v_mfma_f32_16x16x32_bf16 v[24:27], v[152:155], v[196:199], v[24:27]
	v_mfma_f32_16x16x32_bf16 v[12:15], v[144:147], v[204:207], v[12:15]
	v_mfma_f32_16x16x32_bf16 v[8:11], v[152:155], v[204:207], v[8:11]
	v_mfma_f32_16x16x32_bf16 v[60:63], v[148:151], v[180:183], v[60:63]
	v_mfma_f32_16x16x32_bf16 v[56:59], v[156:159], v[180:183], v[56:59]
	v_mfma_f32_16x16x32_bf16 v[44:47], v[148:151], v[188:191], v[44:47]
	v_mfma_f32_16x16x32_bf16 v[40:43], v[156:159], v[188:191], v[40:43]
	v_mfma_f32_16x16x32_bf16 v[28:31], v[148:151], v[200:203], v[28:31]
	v_mfma_f32_16x16x32_bf16 v[24:27], v[156:159], v[200:203], v[24:27]
	v_mfma_f32_16x16x32_bf16 v[12:15], v[148:151], v[208:211], v[12:15]
	v_mfma_f32_16x16x32_bf16 v[8:11], v[156:159], v[208:211], v[8:11]
	s_setprio 0
	s_setprio 1
	v_mfma_f32_16x16x32_bf16 v[52:55], v[160:163], v[176:179], v[52:55]
	v_mfma_f32_16x16x32_bf16 v[48:51], v[168:171], v[176:179], v[48:51]
	v_mfma_f32_16x16x32_bf16 v[36:39], v[160:163], v[184:187], v[36:39]
	v_mfma_f32_16x16x32_bf16 v[32:35], v[168:171], v[184:187], v[32:35]
	v_mfma_f32_16x16x32_bf16 v[20:23], v[160:163], v[196:199], v[20:23]
	v_mfma_f32_16x16x32_bf16 v[16:19], v[168:171], v[196:199], v[16:19]
	v_mfma_f32_16x16x32_bf16 v[4:7], v[160:163], v[204:207], v[4:7]
	v_mfma_f32_16x16x32_bf16 v[0:3], v[168:171], v[204:207], v[0:3]
	v_mfma_f32_16x16x32_bf16 v[52:55], v[164:167], v[180:183], v[52:55]
	v_mfma_f32_16x16x32_bf16 v[48:51], v[172:175], v[180:183], v[48:51]
	v_mfma_f32_16x16x32_bf16 v[36:39], v[164:167], v[188:191], v[36:39]
	v_mfma_f32_16x16x32_bf16 v[32:35], v[172:175], v[188:191], v[32:35]
	v_mfma_f32_16x16x32_bf16 v[20:23], v[164:167], v[200:203], v[20:23]
	v_mfma_f32_16x16x32_bf16 v[16:19], v[172:175], v[200:203], v[16:19]
	v_mfma_f32_16x16x32_bf16 v[4:7], v[164:167], v[208:211], v[4:7]
	v_mfma_f32_16x16x32_bf16 v[0:3], v[172:175], v[208:211], v[0:3]
	s_setprio 0
	s_barrier
	s_add_i32 s53, s53, 2
	s_add_u32 s51, s51, 0x100
	s_addc_u32 s52, s52, 0
	s_add_u32 s30, s30, 0x100
	s_addc_u32 s31, s31, 0
	s_cmp_gt_u32 s53, 13
	s_cbranch_scc0 .LBB0_574
	s_branch .Lpeel_exit_574

.Lpeel_exit_574:
	s_and_b64 vcc, exec, s[20:21]
	s_cbranch_vccz .LBB0_577
	s_barrier

.LBB0_667:
	s_add_u32 s51, s52, 0x100
	s_addc_u32 s74, s53, 0
	s_add_u32 s12, s54, 0x80
	s_waitcnt vmcnt(0)
	s_addc_u32 s13, s55, 0
	s_mov_b32 s52, 0
	s_nop 0
	s_add_i32 s54, s52, 2
	s_add_u32 s55, s12, 0x80
	s_addc_u32 s53, s13, 0
	s_add_i32 s75, 0, 0x10000
	s_cmp_eq_u32 s73, s52
	s_cselect_b32 s53, s47, s53
	s_cselect_b32 s52, s46, s55
	s_cselect_b32 s83, s49, s74
	s_cselect_b32 s82, s48, s51
	s_add_i32 s55, 0, 0x14000
	v_add_u32_e32 v140, s75, v203
	v_add_u32_e32 v156, s55, v203
	ds_read_b128 v[128:131], v140
	ds_read_b128 v[132:135], v140 offset:1024
	ds_read_b128 v[136:139], v140 offset:2048
	ds_read_b128 v[140:143], v140 offset:3072
	ds_read_b128 v[144:147], v156
	ds_read_b128 v[148:151], v156 offset:1024
	ds_read_b128 v[152:155], v156 offset:2048
	ds_read_b128 v[156:159], v156 offset:3072
	v_lshl_add_u64 v[190:191], s[12:13], 0, v[184:185]
	s_add_i32 m0, s63, 0xc000
	ds_read_b128 v[160:163], v231
	ds_read_b128 v[164:167], v231 offset:1024
	ds_read_b128 v[168:171], v231 offset:2048
	ds_read_b128 v[172:175], v231 offset:3072
	ds_read_b128 v[186:189], v231 offset:4096
	ds_read_b128 v[196:199], v231 offset:5120
	ds_read_b128 v[224:227], v231 offset:6144
	ds_read_b128 v[238:241], v231 offset:7168
	global_load_lds_dwordx4 v[190:191], off
	v_lshl_add_u64 v[190:191], s[12:13], 0, v[182:183]
	s_add_i32 m0, s63, 0xe000
	s_nop 0
	global_load_lds_dwordx4 v[190:191], off
	s_waitcnt vmcnt(8)
	s_waitcnt lgkmcnt(0)
	s_barrier
	s_setprio 1
	s_waitcnt lgkmcnt(0)
	v_mfma_f32_16x16x32_bf16 v[68:71], v[128:131], v[160:163], 0
	v_mfma_f32_16x16x32_bf16 v[72:75], v[136:139], v[160:163], 0
	v_mfma_f32_16x16x32_bf16 v[8:11], v[128:131], v[168:171], 0
	v_mfma_f32_16x16x32_bf16 v[16:19], v[136:139], v[168:171], 0
	v_mfma_f32_16x16x32_bf16 v[56:59], v[128:131], v[186:189], 0
	v_mfma_f32_16x16x32_bf16 v[60:63], v[136:139], v[186:189], 0
	v_mfma_f32_16x16x32_bf16 v[36:39], v[128:131], v[224:227], 0
	v_mfma_f32_16x16x32_bf16 v[44:47], v[136:139], v[224:227], 0
	v_mfma_f32_16x16x32_bf16 v[68:71], v[132:135], v[164:167], v[68:71]
	v_mfma_f32_16x16x32_bf16 v[72:75], v[140:143], v[164:167], v[72:75]
	v_mfma_f32_16x16x32_bf16 v[8:11], v[132:135], v[172:175], v[8:11]
	v_mfma_f32_16x16x32_bf16 v[16:19], v[140:143], v[172:175], v[16:19]
	v_mfma_f32_16x16x32_bf16 v[56:59], v[132:135], v[196:199], v[56:59]
	v_mfma_f32_16x16x32_bf16 v[60:63], v[140:143], v[196:199], v[60:63]
	v_mfma_f32_16x16x32_bf16 v[36:39], v[132:135], v[238:241], v[36:39]
	v_mfma_f32_16x16x32_bf16 v[44:47], v[140:143], v[238:241], v[44:47]
	s_setprio 0
	s_setprio 1
	v_mfma_f32_16x16x32_bf16 v[12:15], v[144:147], v[160:163], 0
	v_mfma_f32_16x16x32_bf16 v[20:23], v[152:155], v[160:163], 0
	v_mfma_f32_16x16x32_bf16 v[0:3], v[144:147], v[168:171], 0
	v_mfma_f32_16x16x32_bf16 v[4:7], v[152:155], v[168:171], 0
	v_mfma_f32_16x16x32_bf16 v[32:35], v[144:147], v[186:189], 0
	v_mfma_f32_16x16x32_bf16 v[40:43], v[152:155], v[186:189], 0
	v_mfma_f32_16x16x32_bf16 v[24:27], v[144:147], v[224:227], 0
	v_mfma_f32_16x16x32_bf16 v[28:31], v[152:155], v[224:227], 0
	v_mfma_f32_16x16x32_bf16 v[12:15], v[148:151], v[164:167], v[12:15]
	v_mfma_f32_16x16x32_bf16 v[20:23], v[156:159], v[164:167], v[20:23]
	v_mfma_f32_16x16x32_bf16 v[0:3], v[148:151], v[172:175], v[0:3]
	v_mfma_f32_16x16x32_bf16 v[4:7], v[156:159], v[172:175], v[4:7]
	v_mfma_f32_16x16x32_bf16 v[32:35], v[148:151], v[196:199], v[32:35]
	v_mfma_f32_16x16x32_bf16 v[40:43], v[156:159], v[196:199], v[40:43]
	v_mfma_f32_16x16x32_bf16 v[24:27], v[148:151], v[238:241], v[24:27]
	v_mfma_f32_16x16x32_bf16 v[28:31], v[156:159], v[238:241], v[28:31]
	s_setprio 0
	s_barrier
	s_add_i32 s75, s75, s62
	v_lshl_add_u64 v[190:191], s[82:83], 0, v[192:193]
	s_mov_b32 m0, s75
	ds_read_b128 v[160:163], v231 offset:16384
	ds_read_b128 v[164:167], v231 offset:17408
	ds_read_b128 v[168:171], v231 offset:18432
	ds_read_b128 v[172:175], v231 offset:19456
	ds_read_b128 v[186:189], v231 offset:20480
	ds_read_b128 v[196:199], v231 offset:21504
	ds_read_b128 v[224:227], v231 offset:22528
	ds_read_b128 v[238:241], v231 offset:23552
	global_load_lds_dwordx4 v[190:191], off
	s_add_i32 m0, s75, 0x2000
	v_lshl_add_u64 v[200:201], s[82:83], 0, v[176:177]
	s_add_u32 s82, s82, s80
	s_addc_u32 s83, s83, 0
	s_add_i32 s55, s55, s62
	global_load_lds_dwordx4 v[200:201], off
	v_lshl_add_u64 v[234:235], s[82:83], 0, v[192:193]
	s_mov_b32 m0, s55
	v_lshl_add_u64 v[242:243], s[82:83], 0, v[176:177]
	global_load_lds_dwordx4 v[234:235], off
	s_add_i32 m0, s55, 0x2000
	v_lshl_add_u64 v[244:245], s[52:53], 0, v[180:181]
	global_load_lds_dwordx4 v[242:243], off
	s_mov_b32 m0, s63
	v_lshl_add_u64 v[246:247], s[52:53], 0, v[178:179]
	global_load_lds_dwordx4 v[244:245], off
	s_mov_b32 m0, s64
	s_nop 0
	global_load_lds_dwordx4 v[246:247], off
	s_waitcnt vmcnt(8)
	s_waitcnt lgkmcnt(0)
	s_barrier
	s_setprio 1
	s_waitcnt lgkmcnt(0)
	v_mfma_f32_16x16x32_bf16 v[88:91], v[128:131], v[160:163], 0
	v_mfma_f32_16x16x32_bf16 v[92:95], v[136:139], v[160:163], 0
	v_mfma_f32_16x16x32_bf16 v[76:79], v[128:131], v[168:171], 0
	v_mfma_f32_16x16x32_bf16 v[84:87], v[136:139], v[168:171], 0
	v_mfma_f32_16x16x32_bf16 v[120:123], v[128:131], v[186:189], 0
	v_mfma_f32_16x16x32_bf16 v[124:127], v[136:139], v[186:189], 0
	v_mfma_f32_16x16x32_bf16 v[108:111], v[128:131], v[224:227], 0
	v_mfma_f32_16x16x32_bf16 v[116:119], v[136:139], v[224:227], 0
	v_mfma_f32_16x16x32_bf16 v[88:91], v[132:135], v[164:167], v[88:91]
	v_mfma_f32_16x16x32_bf16 v[92:95], v[140:143], v[164:167], v[92:95]
	v_mfma_f32_16x16x32_bf16 v[76:79], v[132:135], v[172:175], v[76:79]
	v_mfma_f32_16x16x32_bf16 v[84:87], v[140:143], v[172:175], v[84:87]
	v_mfma_f32_16x16x32_bf16 v[120:123], v[132:135], v[196:199], v[120:123]
	v_mfma_f32_16x16x32_bf16 v[124:127], v[140:143], v[196:199], v[124:127]
	v_mfma_f32_16x16x32_bf16 v[108:111], v[132:135], v[238:241], v[108:111]
	v_mfma_f32_16x16x32_bf16 v[116:119], v[140:143], v[238:241], v[116:119]
	s_setprio 0
	s_setprio 1
	v_mfma_f32_16x16x32_bf16 v[64:67], v[144:147], v[160:163], 0
	v_mfma_f32_16x16x32_bf16 v[80:83], v[152:155], v[160:163], 0
	v_mfma_f32_16x16x32_bf16 v[48:51], v[144:147], v[168:171], 0
	v_mfma_f32_16x16x32_bf16 v[52:55], v[152:155], v[168:171], 0
	v_mfma_f32_16x16x32_bf16 v[104:107], v[144:147], v[186:189], 0
	v_mfma_f32_16x16x32_bf16 v[112:115], v[152:155], v[186:189], 0
	v_mfma_f32_16x16x32_bf16 v[96:99], v[144:147], v[224:227], 0
	v_mfma_f32_16x16x32_bf16 v[100:103], v[152:155], v[224:227], 0
	v_mfma_f32_16x16x32_bf16 v[64:67], v[148:151], v[164:167], v[64:67]
	v_mfma_f32_16x16x32_bf16 v[80:83], v[156:159], v[164:167], v[80:83]
	v_mfma_f32_16x16x32_bf16 v[48:51], v[148:151], v[172:175], v[48:51]
	v_mfma_f32_16x16x32_bf16 v[52:55], v[156:159], v[172:175], v[52:55]
	v_mfma_f32_16x16x32_bf16 v[104:107], v[148:151], v[196:199], v[104:107]
	v_mfma_f32_16x16x32_bf16 v[112:115], v[156:159], v[196:199], v[112:115]
	v_mfma_f32_16x16x32_bf16 v[96:99], v[148:151], v[238:241], v[96:99]
	v_mfma_f32_16x16x32_bf16 v[100:103], v[156:159], v[238:241], v[100:103]
	s_setprio 0
	s_barrier
	s_add_i32 s55, 0, 0x18000
	s_add_i32 s75, 0, 0x1c000
	v_add_u32_e32 v140, s55, v203
	v_add_u32_e32 v156, s75, v203
	ds_read_b128 v[128:131], v140
	ds_read_b128 v[132:135], v140 offset:1024
	ds_read_b128 v[136:139], v140 offset:2048
	ds_read_b128 v[140:143], v140 offset:3072
	ds_read_b128 v[144:147], v156
	ds_read_b128 v[148:151], v156 offset:1024
	ds_read_b128 v[152:155], v156 offset:2048
	ds_read_b128 v[156:159], v156 offset:3072
	s_add_u32 s52, s52, s80
	s_addc_u32 s53, s53, 0
	s_mov_b32 m0, s65
	v_lshl_add_u64 v[248:249], s[52:53], 0, v[180:181]
	ds_read_b128 v[160:163], v231 offset:32768
	ds_read_b128 v[164:167], v231 offset:33792
	ds_read_b128 v[168:171], v231 offset:34816
	ds_read_b128 v[172:175], v231 offset:35840
	ds_read_b128 v[186:189], v231 offset:36864
	ds_read_b128 v[196:199], v231 offset:37888
	ds_read_b128 v[224:227], v231 offset:38912
	ds_read_b128 v[238:241], v231 offset:39936
	global_load_lds_dwordx4 v[248:249], off
	v_lshl_add_u64 v[248:249], s[52:53], 0, v[178:179]
	s_mov_b32 m0, s66
	s_nop 0
	global_load_lds_dwordx4 v[248:249], off
	s_waitcnt vmcnt(8)
	s_waitcnt lgkmcnt(0)
	s_barrier
	s_setprio 1
	s_waitcnt lgkmcnt(0)
	v_mfma_f32_16x16x32_bf16 v[68:71], v[128:131], v[160:163], v[68:71]
	v_mfma_f32_16x16x32_bf16 v[72:75], v[136:139], v[160:163], v[72:75]
	v_mfma_f32_16x16x32_bf16 v[8:11], v[128:131], v[168:171], v[8:11]
	v_mfma_f32_16x16x32_bf16 v[16:19], v[136:139], v[168:171], v[16:19]
	v_mfma_f32_16x16x32_bf16 v[56:59], v[128:131], v[186:189], v[56:59]
	v_mfma_f32_16x16x32_bf16 v[60:63], v[136:139], v[186:189], v[60:63]
	v_mfma_f32_16x16x32_bf16 v[36:39], v[128:131], v[224:227], v[36:39]
	v_mfma_f32_16x16x32_bf16 v[44:47], v[136:139], v[224:227], v[44:47]
	v_mfma_f32_16x16x32_bf16 v[68:71], v[132:135], v[164:167], v[68:71]
	v_mfma_f32_16x16x32_bf16 v[72:75], v[140:143], v[164:167], v[72:75]
	v_mfma_f32_16x16x32_bf16 v[8:11], v[132:135], v[172:175], v[8:11]
	v_mfma_f32_16x16x32_bf16 v[16:19], v[140:143], v[172:175], v[16:19]
	v_mfma_f32_16x16x32_bf16 v[56:59], v[132:135], v[196:199], v[56:59]
	v_mfma_f32_16x16x32_bf16 v[60:63], v[140:143], v[196:199], v[60:63]
	v_mfma_f32_16x16x32_bf16 v[36:39], v[132:135], v[238:241], v[36:39]
	v_mfma_f32_16x16x32_bf16 v[44:47], v[140:143], v[238:241], v[44:47]
	s_setprio 0
	s_setprio 1
	v_mfma_f32_16x16x32_bf16 v[12:15], v[144:147], v[160:163], v[12:15]
	v_mfma_f32_16x16x32_bf16 v[20:23], v[152:155], v[160:163], v[20:23]
	v_mfma_f32_16x16x32_bf16 v[0:3], v[144:147], v[168:171], v[0:3]
	v_mfma_f32_16x16x32_bf16 v[4:7], v[152:155], v[168:171], v[4:7]
	v_mfma_f32_16x16x32_bf16 v[32:35], v[144:147], v[186:189], v[32:35]
	v_mfma_f32_16x16x32_bf16 v[40:43], v[152:155], v[186:189], v[40:43]
	v_mfma_f32_16x16x32_bf16 v[24:27], v[144:147], v[224:227], v[24:27]
	v_mfma_f32_16x16x32_bf16 v[28:31], v[152:155], v[224:227], v[28:31]
	v_mfma_f32_16x16x32_bf16 v[12:15], v[148:151], v[164:167], v[12:15]
	v_mfma_f32_16x16x32_bf16 v[20:23], v[156:159], v[164:167], v[20:23]
	v_mfma_f32_16x16x32_bf16 v[0:3], v[148:151], v[172:175], v[0:3]
	v_mfma_f32_16x16x32_bf16 v[4:7], v[156:159], v[172:175], v[4:7]
	v_mfma_f32_16x16x32_bf16 v[32:35], v[148:151], v[196:199], v[32:35]
	v_mfma_f32_16x16x32_bf16 v[40:43], v[156:159], v[196:199], v[40:43]
	v_mfma_f32_16x16x32_bf16 v[24:27], v[148:151], v[238:241], v[24:27]
	v_mfma_f32_16x16x32_bf16 v[28:31], v[156:159], v[238:241], v[28:31]
	s_setprio 0
	s_barrier
	s_nop 0
	s_add_i32 s52, s55, s62
	v_lshl_add_u64 v[190:191], v[190:191], 0, s[2:3]
	s_mov_b32 m0, s52
	ds_read_b128 v[160:163], v231 offset:49152
	ds_read_b128 v[164:167], v231 offset:50176
	ds_read_b128 v[168:171], v231 offset:51200
	ds_read_b128 v[172:175], v231 offset:52224
	ds_read_b128 v[186:189], v231 offset:53248
	ds_read_b128 v[196:199], v231 offset:54272
	ds_read_b128 v[224:227], v231 offset:55296
	ds_read_b128 v[238:241], v231 offset:56320
	global_load_lds_dwordx4 v[190:191], off
	v_lshl_add_u64 v[190:191], v[200:201], 0, s[2:3]
	s_add_i32 m0, s52, 0x2000
	s_add_i32 s52, s75, s62
	global_load_lds_dwordx4 v[190:191], off
	v_lshl_add_u64 v[190:191], v[234:235], 0, s[2:3]
	s_mov_b32 m0, s52
	s_nop 0
	global_load_lds_dwordx4 v[190:191], off
	v_lshl_add_u64 v[190:191], v[242:243], 0, s[2:3]
	s_add_i32 m0, s52, 0x2000
	s_nop 0
	global_load_lds_dwordx4 v[190:191], off
	v_lshl_add_u64 v[190:191], v[244:245], 0, s[2:3]
	s_mov_b32 m0, s69
	s_nop 0
	global_load_lds_dwordx4 v[190:191], off
	v_lshl_add_u64 v[190:191], v[246:247], 0, s[2:3]
	s_mov_b32 m0, s70
	s_nop 0
	global_load_lds_dwordx4 v[190:191], off
	s_waitcnt vmcnt(8)
	s_waitcnt lgkmcnt(0)
	s_barrier
	s_setprio 1
	s_waitcnt lgkmcnt(0)
	v_mfma_f32_16x16x32_bf16 v[88:91], v[128:131], v[160:163], v[88:91]
	v_mfma_f32_16x16x32_bf16 v[92:95], v[136:139], v[160:163], v[92:95]
	v_mfma_f32_16x16x32_bf16 v[76:79], v[128:131], v[168:171], v[76:79]
	v_mfma_f32_16x16x32_bf16 v[84:87], v[136:139], v[168:171], v[84:87]
	v_mfma_f32_16x16x32_bf16 v[120:123], v[128:131], v[186:189], v[120:123]
	v_mfma_f32_16x16x32_bf16 v[124:127], v[136:139], v[186:189], v[124:127]
	v_mfma_f32_16x16x32_bf16 v[108:111], v[128:131], v[224:227], v[108:111]
	v_mfma_f32_16x16x32_bf16 v[116:119], v[136:139], v[224:227], v[116:119]
	v_mfma_f32_16x16x32_bf16 v[88:91], v[132:135], v[164:167], v[88:91]
	v_mfma_f32_16x16x32_bf16 v[92:95], v[140:143], v[164:167], v[92:95]
	v_mfma_f32_16x16x32_bf16 v[76:79], v[132:135], v[172:175], v[76:79]
	v_mfma_f32_16x16x32_bf16 v[84:87], v[140:143], v[172:175], v[84:87]
	v_mfma_f32_16x16x32_bf16 v[120:123], v[132:135], v[196:199], v[120:123]
	v_mfma_f32_16x16x32_bf16 v[124:127], v[140:143], v[196:199], v[124:127]
	v_mfma_f32_16x16x32_bf16 v[108:111], v[132:135], v[238:241], v[108:111]
	v_mfma_f32_16x16x32_bf16 v[116:119], v[140:143], v[238:241], v[116:119]
	s_setprio 0
	s_setprio 1
	v_mfma_f32_16x16x32_bf16 v[64:67], v[144:147], v[160:163], v[64:67]
	v_mfma_f32_16x16x32_bf16 v[80:83], v[152:155], v[160:163], v[80:83]
	v_mfma_f32_16x16x32_bf16 v[48:51], v[144:147], v[168:171], v[48:51]
	v_mfma_f32_16x16x32_bf16 v[52:55], v[152:155], v[168:171], v[52:55]
	v_mfma_f32_16x16x32_bf16 v[104:107], v[144:147], v[186:189], v[104:107]
	v_mfma_f32_16x16x32_bf16 v[112:115], v[152:155], v[186:189], v[112:115]
	v_mfma_f32_16x16x32_bf16 v[96:99], v[144:147], v[224:227], v[96:99]
	v_mfma_f32_16x16x32_bf16 v[100:103], v[152:155], v[224:227], v[100:103]
	v_mfma_f32_16x16x32_bf16 v[64:67], v[148:151], v[164:167], v[64:67]
	v_mfma_f32_16x16x32_bf16 v[80:83], v[156:159], v[164:167], v[80:83]
	v_mfma_f32_16x16x32_bf16 v[48:51], v[148:151], v[172:175], v[48:51]
	v_mfma_f32_16x16x32_bf16 v[52:55], v[156:159], v[172:175], v[52:55]
	v_mfma_f32_16x16x32_bf16 v[104:107], v[148:151], v[196:199], v[104:107]
	v_mfma_f32_16x16x32_bf16 v[112:115], v[156:159], v[196:199], v[112:115]
	v_mfma_f32_16x16x32_bf16 v[96:99], v[148:151], v[238:241], v[96:99]
	v_mfma_f32_16x16x32_bf16 v[100:103], v[156:159], v[238:241], v[100:103]
	s_setprio 0
	s_barrier
	s_add_u32 s51, s51, 0x100
	s_addc_u32 s74, s74, 0
	s_add_u32 s12, s12, 0x100
	s_addc_u32 s13, s13, 0
	s_cmp_ge_u32 s54, s72
	s_mov_b32 s52, s54
	s_cbranch_scc0 .LBB0_668
	s_branch .Lpeel_exit_668

.Lpeel_exit_668:
	s_and_b64 vcc, exec, s[36:37]
	s_cbranch_vccz .LBB0_671
	s_barrier
